# MLP-up GEMM epilogue: relu-square-pack in place on accumulator quads (no canonicalise, packed squares): 192 fewer VALU per tile and wave
# baseline (speedup 1.0000x reference)
; __device__ __forceinline__ unsigned cvt_pk_bf16(float lo, float hi) { unsigned r; asm volatile("v_cvt_pk_bf16_f32 %0, %1, %2" : "=v"(r) : "v"(lo), "v"(hi)); return r; }
;     __device__ __forceinline__ void operator()(const f32x4 (&acc)[2][2][4][2], const Unit& u, int wr, int wc, int fr, int fq) const {
;     ...
;         const int row0 = u.pm * BM + wr * 64 + fr; const int col0 = u.pn * BM + wc * 32 + 8 * fq;
; #pragma unroll
;         for (int ai = 0; ai < 2; ++ai)
; #pragma unroll
;             for (int m = 0; m < 4; ++m) { bf16_t* rowp = O + (size_t)(row0 + ai * HALF + m * 16) * ldc + col0;
; #pragma unroll
;                 for (int bj = 0; bj < 2; ++bj) { f32x4 v0 = acc[ai][bj][m][0], v1 = acc[ai][bj][m][1];
;                     if (ACT == 1) {
; #pragma unroll
;                         for (int e = 0; e < 4; ++e) { float a = fmaxf(v0[e], 0.f), b = fmaxf(v1[e], 0.f); v0[e] = a * a; v1[e] = b * b; } }
;                     u32x4 w; w.x = cvt_pk_bf16(v0[0], v0[1]); w.y = cvt_pk_bf16(v0[2], v0[3]); w.z = cvt_pk_bf16(v1[0], v1[1]); w.w = cvt_pk_bf16(v1[2], v1[3]);
;                     *(u32x4*)(rowp + bj * HALF) = w; } }
.LBB0_57:
	v_lshl_add_u32 v146, s44, 8, v142
	v_ashrrev_i32_e32 v147, 31, v146
	v_lshl_or_b32 v140, s42, 8, v144
	v_lshlrev_b64 v[148:149], 13, v[146:147]
	v_ashrrev_i32_e32 v141, 31, v140
	v_lshl_add_u64 v[148:149], s[16:17], 0, v[148:149]
	v_lshlrev_b64 v[150:151], 1, v[140:141]
	v_lshl_add_u64 v[140:141], v[148:149], 0, v[150:151]
	v_max_f32_e32 v126, 0, v126
	v_max_f32_e32 v127, 0, v127
	v_max_f32_e32 v128, 0, v128
	v_max_f32_e32 v129, 0, v129
	v_max_f32_e32 v122, 0, v122
	v_max_f32_e32 v123, 0, v123
	v_max_f32_e32 v124, 0, v124
	v_max_f32_e32 v125, 0, v125
	v_pk_mul_f32 v[126:127], v[126:127], v[126:127]
	v_pk_mul_f32 v[128:129], v[128:129], v[128:129]
	v_pk_mul_f32 v[122:123], v[122:123], v[122:123]
	v_pk_mul_f32 v[124:125], v[124:125], v[124:125]
	v_cvt_pk_bf16_f32 v126, v126, v127
	v_cvt_pk_bf16_f32 v127, v128, v129
	v_cvt_pk_bf16_f32 v128, v122, v123
	v_cvt_pk_bf16_f32 v129, v124, v125
	global_store_dwordx4 v[140:141], v[126:129], off
	v_max_f32_e32 v118, 0, v118
	v_max_f32_e32 v119, 0, v119
	v_max_f32_e32 v120, 0, v120
	v_max_f32_e32 v121, 0, v121
	v_max_f32_e32 v114, 0, v114
	v_max_f32_e32 v115, 0, v115
	v_max_f32_e32 v116, 0, v116
	v_max_f32_e32 v117, 0, v117
	v_pk_mul_f32 v[118:119], v[118:119], v[118:119]
	v_pk_mul_f32 v[120:121], v[120:121], v[120:121]
	v_pk_mul_f32 v[114:115], v[114:115], v[114:115]
	v_pk_mul_f32 v[116:117], v[116:117], v[116:117]
	v_cvt_pk_bf16_f32 v118, v118, v119
	v_cvt_pk_bf16_f32 v119, v120, v121
	v_cvt_pk_bf16_f32 v120, v114, v115
	v_cvt_pk_bf16_f32 v121, v116, v117
	global_store_dwordx4 v[140:141], v[118:121], off offset:256
	v_or_b32_e32 v114, 16, v146
	v_ashrrev_i32_e32 v115, 31, v114
	v_lshlrev_b64 v[114:115], 13, v[114:115]
	v_lshl_add_u64 v[114:115], s[16:17], 0, v[114:115]
	v_lshl_add_u64 v[114:115], v[114:115], 0, v[150:151]
	v_max_f32_e32 v110, 0, v110
	v_max_f32_e32 v111, 0, v111
	v_max_f32_e32 v112, 0, v112
	v_max_f32_e32 v113, 0, v113
	v_max_f32_e32 v106, 0, v106
	v_max_f32_e32 v107, 0, v107
	v_max_f32_e32 v108, 0, v108
	v_max_f32_e32 v109, 0, v109
	v_pk_mul_f32 v[110:111], v[110:111], v[110:111]
	v_pk_mul_f32 v[112:113], v[112:113], v[112:113]
	v_pk_mul_f32 v[106:107], v[106:107], v[106:107]
	v_pk_mul_f32 v[108:109], v[108:109], v[108:109]
	v_cvt_pk_bf16_f32 v110, v110, v111
	v_cvt_pk_bf16_f32 v111, v112, v113
	v_cvt_pk_bf16_f32 v112, v106, v107
	v_cvt_pk_bf16_f32 v113, v108, v109
	global_store_dwordx4 v[114:115], v[110:113], off
	v_max_f32_e32 v102, 0, v102
	v_max_f32_e32 v103, 0, v103
	v_max_f32_e32 v104, 0, v104
	v_max_f32_e32 v105, 0, v105
	v_max_f32_e32 v98, 0, v98
	v_max_f32_e32 v99, 0, v99
	v_max_f32_e32 v100, 0, v100
	v_max_f32_e32 v101, 0, v101
	v_pk_mul_f32 v[102:103], v[102:103], v[102:103]
	v_pk_mul_f32 v[104:105], v[104:105], v[104:105]
	v_pk_mul_f32 v[98:99], v[98:99], v[98:99]
	v_pk_mul_f32 v[100:101], v[100:101], v[100:101]
	v_cvt_pk_bf16_f32 v102, v102, v103
	v_cvt_pk_bf16_f32 v103, v104, v105
	v_cvt_pk_bf16_f32 v104, v98, v99
	v_cvt_pk_bf16_f32 v105, v100, v101
	global_store_dwordx4 v[114:115], v[102:105], off offset:256
	v_or_b32_e32 v98, 32, v146
	v_ashrrev_i32_e32 v99, 31, v98
	v_lshlrev_b64 v[98:99], 13, v[98:99]
	v_lshl_add_u64 v[98:99], s[16:17], 0, v[98:99]
	v_lshl_add_u64 v[98:99], v[98:99], 0, v[150:151]
	v_max_f32_e32 v94, 0, v94
	v_max_f32_e32 v95, 0, v95
	v_max_f32_e32 v96, 0, v96
	v_max_f32_e32 v97, 0, v97
	v_max_f32_e32 v90, 0, v90
	v_max_f32_e32 v91, 0, v91
	v_max_f32_e32 v92, 0, v92
	v_max_f32_e32 v93, 0, v93
	v_pk_mul_f32 v[94:95], v[94:95], v[94:95]
	v_pk_mul_f32 v[96:97], v[96:97], v[96:97]
	v_pk_mul_f32 v[90:91], v[90:91], v[90:91]
	v_pk_mul_f32 v[92:93], v[92:93], v[92:93]
	v_cvt_pk_bf16_f32 v94, v94, v95
	v_cvt_pk_bf16_f32 v95, v96, v97
	v_cvt_pk_bf16_f32 v96, v90, v91
	v_cvt_pk_bf16_f32 v97, v92, v93
	global_store_dwordx4 v[98:99], v[94:97], off
	v_max_f32_e32 v86, 0, v86
	v_max_f32_e32 v87, 0, v87
	v_max_f32_e32 v88, 0, v88
	v_max_f32_e32 v89, 0, v89
	v_max_f32_e32 v82, 0, v82
	v_max_f32_e32 v83, 0, v83
	v_max_f32_e32 v84, 0, v84
	v_max_f32_e32 v85, 0, v85
	v_pk_mul_f32 v[86:87], v[86:87], v[86:87]
	v_pk_mul_f32 v[88:89], v[88:89], v[88:89]
	v_pk_mul_f32 v[82:83], v[82:83], v[82:83]
	v_pk_mul_f32 v[84:85], v[84:85], v[84:85]
	v_cvt_pk_bf16_f32 v86, v86, v87
	v_cvt_pk_bf16_f32 v87, v88, v89
	v_cvt_pk_bf16_f32 v88, v82, v83
	v_cvt_pk_bf16_f32 v89, v84, v85
	global_store_dwordx4 v[98:99], v[86:89], off offset:256
	v_or_b32_e32 v82, 48, v146
	v_ashrrev_i32_e32 v83, 31, v82
	v_lshlrev_b64 v[82:83], 13, v[82:83]
	v_lshl_add_u64 v[82:83], s[16:17], 0, v[82:83]
	v_lshl_add_u64 v[82:83], v[82:83], 0, v[150:151]
	v_max_f32_e32 v78, 0, v78
	v_max_f32_e32 v79, 0, v79
	v_max_f32_e32 v80, 0, v80
	v_max_f32_e32 v81, 0, v81
	v_max_f32_e32 v74, 0, v74
	v_max_f32_e32 v75, 0, v75
	v_max_f32_e32 v76, 0, v76
	v_max_f32_e32 v77, 0, v77
	v_pk_mul_f32 v[78:79], v[78:79], v[78:79]
	v_pk_mul_f32 v[80:81], v[80:81], v[80:81]
	v_pk_mul_f32 v[74:75], v[74:75], v[74:75]
	v_pk_mul_f32 v[76:77], v[76:77], v[76:77]
	v_cvt_pk_bf16_f32 v78, v78, v79
	v_cvt_pk_bf16_f32 v79, v80, v81
	v_cvt_pk_bf16_f32 v80, v74, v75
	v_cvt_pk_bf16_f32 v81, v76, v77
	global_store_dwordx4 v[82:83], v[78:81], off
	v_max_f32_e32 v70, 0, v70
	v_max_f32_e32 v71, 0, v71
	v_max_f32_e32 v72, 0, v72
	v_max_f32_e32 v73, 0, v73
	v_max_f32_e32 v66, 0, v66
	v_max_f32_e32 v67, 0, v67
	v_max_f32_e32 v68, 0, v68
	v_max_f32_e32 v69, 0, v69
	v_pk_mul_f32 v[70:71], v[70:71], v[70:71]
	v_pk_mul_f32 v[72:73], v[72:73], v[72:73]
	v_pk_mul_f32 v[66:67], v[66:67], v[66:67]
	v_pk_mul_f32 v[68:69], v[68:69], v[68:69]
	v_cvt_pk_bf16_f32 v70, v70, v71
	v_cvt_pk_bf16_f32 v71, v72, v73
	v_cvt_pk_bf16_f32 v72, v66, v67
; __device__ __forceinline__ unsigned cvt_pk_bf16(float lo, float hi) { unsigned r; asm volatile("v_cvt_pk_bf16_f32 %0, %1, %2" : "=v"(r) : "v"(lo), "v"(hi)); return r; }
;     __device__ __forceinline__ void operator()(const f32x4 (&acc)[2][2][4][2], const Unit& u, int wr, int wc, int fr, int fq) const {
;     ...
;         const int row0 = u.pm * BM + wr * 64 + fr; const int col0 = u.pn * BM + wc * 32 + 8 * fq;
; #pragma unroll
;         for (int ai = 0; ai < 2; ++ai)
; #pragma unroll
;             for (int m = 0; m < 4; ++m) { bf16_t* rowp = O + (size_t)(row0 + ai * HALF + m * 16) * ldc + col0;
; #pragma unroll
;                 for (int bj = 0; bj < 2; ++bj) { f32x4 v0 = acc[ai][bj][m][0], v1 = acc[ai][bj][m][1];
;                     if (ACT == 1) {
; #pragma unroll
;                         for (int e = 0; e < 4; ++e) { float a = fmaxf(v0[e], 0.f), b = fmaxf(v1[e], 0.f); v0[e] = a * a; v1[e] = b * b; } }
;                     u32x4 w; w.x = cvt_pk_bf16(v0[0], v0[1]); w.y = cvt_pk_bf16(v0[2], v0[3]); w.z = cvt_pk_bf16(v1[0], v1[1]); w.w = cvt_pk_bf16(v1[2], v1[3]);
;                     *(u32x4*)(rowp + bj * HALF) = w; } }
	v_cvt_pk_bf16_f32 v73, v68, v69
	global_store_dwordx4 v[82:83], v[70:73], off offset:256
	s_mov_b64 s[12:13], 0x100000
	v_lshl_add_u64 v[66:67], v[140:141], 0, s[12:13]
	s_mov_b32 s12, 0x100000
	v_add_co_u32_e32 v160, vcc, s12, v140
	v_addc_co_u32_e32 v161, vcc, 0, v141, vcc
	v_max_f32_e32 v62, 0, v62
	v_max_f32_e32 v63, 0, v63
	v_max_f32_e32 v64, 0, v64
	v_max_f32_e32 v65, 0, v65
	v_max_f32_e32 v58, 0, v58
	v_max_f32_e32 v59, 0, v59
	v_max_f32_e32 v60, 0, v60
	v_max_f32_e32 v61, 0, v61
	v_pk_mul_f32 v[62:63], v[62:63], v[62:63]
	v_pk_mul_f32 v[64:65], v[64:65], v[64:65]
	v_pk_mul_f32 v[58:59], v[58:59], v[58:59]
	v_pk_mul_f32 v[60:61], v[60:61], v[60:61]
	v_cvt_pk_bf16_f32 v62, v62, v63
	v_cvt_pk_bf16_f32 v63, v64, v65
	v_cvt_pk_bf16_f32 v64, v58, v59
	v_cvt_pk_bf16_f32 v65, v60, v61
	global_store_dwordx4 v[160:161], v[62:65], off
	v_max_f32_e32 v54, 0, v54
	v_max_f32_e32 v55, 0, v55
	v_max_f32_e32 v56, 0, v56
	v_max_f32_e32 v57, 0, v57
	v_max_f32_e32 v50, 0, v50
	v_max_f32_e32 v51, 0, v51
	v_max_f32_e32 v52, 0, v52
	v_max_f32_e32 v53, 0, v53
	v_pk_mul_f32 v[54:55], v[54:55], v[54:55]
	v_pk_mul_f32 v[56:57], v[56:57], v[56:57]
	v_pk_mul_f32 v[50:51], v[50:51], v[50:51]
	v_pk_mul_f32 v[52:53], v[52:53], v[52:53]
	v_cvt_pk_bf16_f32 v54, v54, v55
	v_cvt_pk_bf16_f32 v55, v56, v57
	v_cvt_pk_bf16_f32 v56, v50, v51
	v_cvt_pk_bf16_f32 v57, v52, v53
	global_store_dwordx4 v[66:67], v[54:57], off offset:256
	s_mov_b64 s[12:13], 0x120000
	v_lshl_add_u64 v[50:51], v[140:141], 0, s[12:13]
	s_mov_b32 s12, 0x120000
	v_add_co_u32_e32 v162, vcc, s12, v140
	v_addc_co_u32_e32 v163, vcc, 0, v141, vcc
	v_max_f32_e32 v46, 0, v46
	v_max_f32_e32 v47, 0, v47
	v_max_f32_e32 v48, 0, v48
	v_max_f32_e32 v49, 0, v49
	v_max_f32_e32 v42, 0, v42
	v_max_f32_e32 v43, 0, v43
	v_max_f32_e32 v44, 0, v44
	v_max_f32_e32 v45, 0, v45
	v_pk_mul_f32 v[46:47], v[46:47], v[46:47]
	v_pk_mul_f32 v[48:49], v[48:49], v[48:49]
	v_pk_mul_f32 v[42:43], v[42:43], v[42:43]
	v_pk_mul_f32 v[44:45], v[44:45], v[44:45]
	v_cvt_pk_bf16_f32 v46, v46, v47
	v_cvt_pk_bf16_f32 v47, v48, v49
	v_cvt_pk_bf16_f32 v48, v42, v43
	v_cvt_pk_bf16_f32 v49, v44, v45
	global_store_dwordx4 v[162:163], v[46:49], off
	v_max_f32_e32 v38, 0, v38
	v_max_f32_e32 v39, 0, v39
	v_max_f32_e32 v40, 0, v40
	v_max_f32_e32 v41, 0, v41
	v_max_f32_e32 v34, 0, v34
	v_max_f32_e32 v35, 0, v35
	v_max_f32_e32 v36, 0, v36
	v_max_f32_e32 v37, 0, v37
	v_pk_mul_f32 v[38:39], v[38:39], v[38:39]
	v_pk_mul_f32 v[40:41], v[40:41], v[40:41]
	v_pk_mul_f32 v[34:35], v[34:35], v[34:35]
	v_pk_mul_f32 v[36:37], v[36:37], v[36:37]
	v_cvt_pk_bf16_f32 v38, v38, v39
	v_cvt_pk_bf16_f32 v39, v40, v41
	v_cvt_pk_bf16_f32 v40, v34, v35
	v_cvt_pk_bf16_f32 v41, v36, v37
	global_store_dwordx4 v[50:51], v[38:41], off offset:256
	s_mov_b64 s[12:13], 0x140000
	v_lshl_add_u64 v[34:35], v[140:141], 0, s[12:13]
	s_mov_b32 s12, 0x140000
	v_add_co_u32_e32 v164, vcc, s12, v140
	v_addc_co_u32_e32 v165, vcc, 0, v141, vcc
	v_max_f32_e32 v30, 0, v30
	v_max_f32_e32 v31, 0, v31
	v_max_f32_e32 v32, 0, v32
	v_max_f32_e32 v33, 0, v33
	v_max_f32_e32 v26, 0, v26
	v_max_f32_e32 v27, 0, v27
	v_max_f32_e32 v28, 0, v28
	v_max_f32_e32 v29, 0, v29
	v_pk_mul_f32 v[30:31], v[30:31], v[30:31]
	v_pk_mul_f32 v[32:33], v[32:33], v[32:33]
	v_pk_mul_f32 v[26:27], v[26:27], v[26:27]
	v_pk_mul_f32 v[28:29], v[28:29], v[28:29]
	v_cvt_pk_bf16_f32 v30, v30, v31
	v_cvt_pk_bf16_f32 v31, v32, v33
	v_cvt_pk_bf16_f32 v32, v26, v27
	v_cvt_pk_bf16_f32 v33, v28, v29
	global_store_dwordx4 v[164:165], v[30:33], off
	v_max_f32_e32 v22, 0, v22
	v_max_f32_e32 v23, 0, v23
	v_max_f32_e32 v24, 0, v24
	v_max_f32_e32 v25, 0, v25
	v_max_f32_e32 v18, 0, v18
	v_max_f32_e32 v19, 0, v19
	v_max_f32_e32 v20, 0, v20
	v_max_f32_e32 v21, 0, v21
	v_pk_mul_f32 v[22:23], v[22:23], v[22:23]
	v_pk_mul_f32 v[24:25], v[24:25], v[24:25]
	v_pk_mul_f32 v[18:19], v[18:19], v[18:19]
	v_pk_mul_f32 v[20:21], v[20:21], v[20:21]
	v_cvt_pk_bf16_f32 v22, v22, v23
	v_cvt_pk_bf16_f32 v23, v24, v25
	v_cvt_pk_bf16_f32 v24, v18, v19
	v_cvt_pk_bf16_f32 v25, v20, v21
	global_store_dwordx4 v[34:35], v[22:25], off offset:256
	s_mov_b64 s[12:13], 0x160000
	v_lshl_add_u64 v[18:19], v[140:141], 0, s[12:13]
	s_mov_b32 s12, 0x160000
	v_add_co_u32_e32 v166, vcc, s12, v140
	v_addc_co_u32_e32 v167, vcc, 0, v141, vcc
	v_max_f32_e32 v14, 0, v14
	v_max_f32_e32 v15, 0, v15
	v_max_f32_e32 v16, 0, v16
	v_max_f32_e32 v17, 0, v17
	v_max_f32_e32 v10, 0, v10
	v_max_f32_e32 v11, 0, v11
	v_max_f32_e32 v12, 0, v12
	v_max_f32_e32 v13, 0, v13
	v_pk_mul_f32 v[14:15], v[14:15], v[14:15]
	v_pk_mul_f32 v[16:17], v[16:17], v[16:17]
	v_pk_mul_f32 v[10:11], v[10:11], v[10:11]
	v_pk_mul_f32 v[12:13], v[12:13], v[12:13]
	v_cvt_pk_bf16_f32 v14, v14, v15
	v_cvt_pk_bf16_f32 v15, v16, v17
	v_cvt_pk_bf16_f32 v16, v10, v11
	v_cvt_pk_bf16_f32 v17, v12, v13
	global_store_dwordx4 v[166:167], v[14:17], off
	v_readlane_b32 s58, v255, 8
	s_andn2_b64 vcc, exec, s[38:39]
	s_mov_b64 s[12:13], -1
	v_readlane_b32 s35, v254, 59
	v_readlane_b32 s43, v254, 60
	v_readlane_b32 s59, v255, 9
	v_max_f32_e32 v6, 0, v6
	v_max_f32_e32 v7, 0, v7
	v_max_f32_e32 v8, 0, v8
	v_max_f32_e32 v9, 0, v9
	v_max_f32_e32 v2, 0, v2
	v_max_f32_e32 v3, 0, v3
	v_max_f32_e32 v4, 0, v4
	v_max_f32_e32 v5, 0, v5
	v_pk_mul_f32 v[6:7], v[6:7], v[6:7]
	v_pk_mul_f32 v[8:9], v[8:9], v[8:9]
	v_pk_mul_f32 v[2:3], v[2:3], v[2:3]
	v_pk_mul_f32 v[4:5], v[4:5], v[4:5]
	v_cvt_pk_bf16_f32 v6, v6, v7
	v_cvt_pk_bf16_f32 v7, v8, v9
	v_cvt_pk_bf16_f32 v8, v2, v3
	v_cvt_pk_bf16_f32 v9, v4, v5
	global_store_dwordx4 v[18:19], v[6:9], off offset:256
	s_cbranch_vccnz .LBB0_50
	s_andn2_b64 vcc, exec, s[26:27]
	s_cbranch_vccnz .LBB0_49
	s_barrier
	s_branch .LBB0_49
